# F with 12 bytes of entry padding (code placement check)
# speedup vs baseline: 1.0056x; 1.0056x over previous
; #define LAS __attribute__((address_space(3)))
; __global__ void __launch_bounds__(NTHR, 2) fwd_megakernel(Args args) {
;     extern __shared__ __attribute__((aligned(16))) unsigned char lds_raw[];
;     LAS unsigned char* lds = (LAS unsigned char*)lds_raw;
;     cg::grid_group grid = cg::this_grid();
;     if (gridDim.x == 0x7fffffffu) grid.sync();
;     { volatile LAS unsigned* mz = (volatile LAS unsigned*)(lds + LDS_BYTES - 64); if (threadIdx.x < 16) mz[threadIdx.x] = 0u; }
_Z14fwd_megakernel4Args:
	s_nop 0
	s_nop 0
	s_nop 0
	s_load_dwordx2 s[6:7], s[0:1], 0x90
	s_load_dwordx16 s[68:83], s[0:1], 0x0
	s_load_dwordx16 s[52:67], s[0:1], 0x40
	s_add_u32 s8, s0, 0x90
	s_addc_u32 s9, s1, 0
	s_waitcnt lgkmcnt(0)
	s_cmp_eq_u32 s6, 0x7fffffff
	s_cbranch_scc1 .LBB0_2
	v_and_b32_e32 v216, 0x3ff, v0
	s_load_dword s3, s[0:1], 0x98
	s_cbranch_execz .LBB0_3
	s_branch .LBB0_14
